# NSA pass1 K-read batching; moba_own K/V ds_read prefetch; NSA union bitmap: 4 serialized 32-lane readlane loops replaced by DPP row OR-reduction
# speedup vs baseline: 1.0235x; 1.0063x over previous
; #define MFMA32(a, b, c) __builtin_amdgcn_mfma_f32_32x32x16_bf16((a), (b), (c), 0, 0, 0)
; DI void qk_tile(const u16* Ks, const bf16x8* qf, f32x16* s, int rl, int hh) {
; #pragma unroll
;   for (int kb = 0; kb < 2; ++kb) {
; #pragma unroll
;     for (int i = 0; i < 16; ++i) s[kb][i] = 0.f;
; #pragma unroll
;     for (int ks = 0; ks < 4; ++ks) {
;       bf16x8 a = *(const bf16x8*)(Ks + (kb * 32 + rl) * KVS + ks * 16 + hh * 8);
;       s[kb] = MFMA32(a, qf[ks], s[kb]);
;     }
;   }
; }
; template <int MODE>
; DI void osm(f32x16* s, uint32_t vm, float& m, float& l, f32x16* o) {
;   float mx = -1e30f;
; #pragma unroll
;   for (int kb = 0; kb < 2; ++kb)
; #pragma unroll
;     for (int i = 0; i < 16; ++i) {
;       if (MODE == 2) s[kb][i] = ((vm >> (kb * 16 + i)) & 1u) ? s[kb][i] : -1e30f;
;       mx = fmaxf(mx, s[kb][i]);
;     }
;   mx *= SCL2;
;   if (MODE == 1) mx = vm ? mx : -1e30f;
.LBB0_795:
	s_or_b64 exec, exec, s[10:11]
	v_cmp_ne_u32_e64 s[10:11], 0, v48
	s_and_b32 s20, s5, 1
	s_mov_b64 vcc, s[10:11]
	s_cbranch_vccz .LBB0_805
	s_mul_i32 s28, s20, 0x4800
	v_or_b32_e32 v32, s28, v120
	v_add_u32_e32 v49, v32, v163
	ds_read_b128 v[50:53], v49
	ds_read_b128 v[54:57], v49 offset:32
	ds_read_b128 v[58:61], v49 offset:64
	ds_read_b128 v[80:83], v49 offset:96
	ds_read_b128 v[32:35], v49 offset:4608
	ds_read_b128 v[84:87], v49 offset:4640
	ds_read_b128 v[88:91], v49 offset:4672
	ds_read_b128 v[92:95], v49 offset:4704
	v_cmp_eq_u32_e32 vcc, -1, v48
	v_cmp_eq_u32_e64 s[12:13], 0, v48
	s_cmp_lg_u64 vcc, -1
	s_waitcnt lgkmcnt(7)
	v_mfma_f32_32x32x16_bf16 v[64:79], v[50:53], v[108:111], 0
	s_waitcnt lgkmcnt(6)
	v_mfma_f32_32x32x16_bf16 v[64:79], v[54:57], v[104:107], v[64:79]
	s_waitcnt lgkmcnt(5)
	v_mfma_f32_32x32x16_bf16 v[64:79], v[58:61], v[100:103], v[64:79]
	s_waitcnt lgkmcnt(4)
	v_mfma_f32_32x32x16_bf16 v[64:79], v[80:83], v[96:99], v[64:79]
	s_waitcnt lgkmcnt(3)
	v_mfma_f32_32x32x16_bf16 v[32:47], v[32:35], v[108:111], 0
	s_waitcnt lgkmcnt(2)
	v_mfma_f32_32x32x16_bf16 v[32:47], v[84:87], v[104:107], v[32:47]
	s_waitcnt lgkmcnt(1)
	v_mfma_f32_32x32x16_bf16 v[32:47], v[88:91], v[100:103], v[32:47]
	s_waitcnt lgkmcnt(0)
	v_mfma_f32_32x32x16_bf16 v[32:47], v[92:95], v[96:99], v[32:47]
	s_cbranch_scc0 .LBB0_808
	s_or_b64 s[12:13], s[12:13], vcc
	s_cmp_lg_u64 s[12:13], -1
	s_cbranch_scc0 .LBB0_809
	v_and_b32_e32 v49, 1, v48
	v_cmp_eq_u32_e32 vcc, 1, v49
	v_and_b32_e32 v50, 2, v48
	v_and_b32_e32 v52, 4, v48
	v_cndmask_b32_e32 v49, v160, v64, vcc
	v_cmp_ne_u32_e32 vcc, 0, v50
	v_and_b32_e32 v53, 8, v48
	v_and_b32_e32 v54, 16, v48
	v_cndmask_b32_e32 v50, v160, v65, vcc
	v_cmp_ne_u32_e32 vcc, 0, v52
	v_and_b32_e32 v55, 32, v48
	v_and_b32_e32 v56, 64, v48
	v_cndmask_b32_e32 v52, v160, v66, vcc
	v_cmp_ne_u32_e32 vcc, 0, v53
	v_and_b32_e32 v57, 0x80, v48
	v_and_b32_e32 v58, 0x100, v48
	v_cndmask_b32_e32 v53, v160, v67, vcc
	v_cmp_ne_u32_e32 vcc, 0, v54
	v_and_b32_e32 v59, 0x200, v48
	v_and_b32_e32 v60, 0x400, v48
	v_cndmask_b32_e32 v54, v160, v68, vcc
	v_cmp_ne_u32_e32 vcc, 0, v55
	v_and_b32_e32 v61, 0x800, v48
	v_and_b32_e32 v62, 0x1000, v48
	v_cndmask_b32_e32 v55, v160, v69, vcc
	v_cmp_ne_u32_e32 vcc, 0, v56
	v_and_b32_e32 v63, 0x2000, v48
	v_and_b32_e32 v80, 0x4000, v48
	v_cndmask_b32_e32 v56, v160, v70, vcc
	v_cmp_ne_u32_e32 vcc, 0, v57
	v_and_b32_e32 v81, 0x8000, v48
	v_and_b32_e32 v82, 0x10000, v48
	v_cndmask_b32_e32 v57, v160, v71, vcc
	v_cmp_ne_u32_e32 vcc, 0, v58
	v_and_b32_e32 v83, 0x20000, v48
	v_and_b32_e32 v84, 0x40000, v48
	v_cndmask_b32_e32 v58, v160, v72, vcc
	v_cmp_ne_u32_e32 vcc, 0, v59
	v_max3_f32 v51, v49, s9, v50
	v_and_b32_e32 v85, 0x80000, v48
	v_cndmask_b32_e32 v59, v160, v73, vcc
	v_cmp_ne_u32_e32 vcc, 0, v60
	v_max3_f32 v51, v51, v52, v53
	v_and_b32_e32 v86, 0x100000, v48
	v_cndmask_b32_e32 v60, v160, v74, vcc
	v_cmp_ne_u32_e32 vcc, 0, v61
	v_max3_f32 v51, v51, v54, v55
	v_and_b32_e32 v87, 0x200000, v48
	v_cndmask_b32_e32 v61, v160, v75, vcc
	v_cmp_ne_u32_e32 vcc, 0, v62
	v_max3_f32 v51, v51, v56, v57
	v_and_b32_e32 v88, 0x400000, v48
	v_cndmask_b32_e32 v62, v160, v76, vcc
	v_cmp_ne_u32_e32 vcc, 0, v63
	v_max3_f32 v51, v51, v58, v59
	v_and_b32_e32 v89, 0x800000, v48
	v_cndmask_b32_e32 v63, v160, v77, vcc
	v_cmp_ne_u32_e32 vcc, 0, v80
	v_max3_f32 v51, v51, v60, v61
	v_and_b32_e32 v90, 0x1000000, v48
	v_cndmask_b32_e32 v80, v160, v78, vcc
	v_cmp_ne_u32_e32 vcc, 0, v81
	v_max3_f32 v51, v51, v62, v63
	v_and_b32_e32 v91, 0x2000000, v48
	v_cndmask_b32_e32 v81, v160, v79, vcc
	v_cmp_ne_u32_e32 vcc, 0, v82
	v_max3_f32 v51, v51, v80, v81
	v_and_b32_e32 v92, 0x4000000, v48
	v_cndmask_b32_e32 v82, v160, v32, vcc
	v_cmp_ne_u32_e32 vcc, 0, v83
	v_and_b32_e32 v93, 0x8000000, v48
	v_and_b32_e32 v94, 0x10000000, v48
	v_cndmask_b32_e32 v83, v160, v33, vcc
	v_cmp_ne_u32_e32 vcc, 0, v84
	v_max3_f32 v51, v51, v82, v83
	v_and_b32_e32 v95, 0x20000000, v48
	v_cndmask_b32_e32 v84, v160, v34, vcc
	v_cmp_ne_u32_e32 vcc, 0, v85
	v_and_b32_e32 v134, 2.0, v48
	s_nop 0
	v_cndmask_b32_e32 v85, v160, v35, vcc
	v_cmp_ne_u32_e32 vcc, 0, v86
	v_max3_f32 v51, v51, v84, v85
	s_nop 0
	v_cndmask_b32_e32 v86, v160, v36, vcc
	v_cmp_ne_u32_e32 vcc, 0, v87
	s_nop 1
	v_cndmask_b32_e32 v87, v160, v37, vcc
	v_cmp_ne_u32_e32 vcc, 0, v88
	v_max3_f32 v51, v51, v86, v87
	s_nop 0
	v_cndmask_b32_e32 v88, v160, v38, vcc
; DI float fexp2(float x) { return __builtin_amdgcn_exp2f(x); }
; template <int MODE>
; DI void osm(f32x16* s, uint32_t vm, float& m, float& l, f32x16* o) {
;     ...
;     for (int i = 0; i < 16; ++i) {
;       if (MODE == 2) s[kb][i] = ((vm >> (kb * 16 + i)) & 1u) ? s[kb][i] : -1e30f;
;       mx = fmaxf(mx, s[kb][i]);
;     }
;   mx *= SCL2;
;   if (MODE == 1) mx = vm ? mx : -1e30f;
;   mx = xmax32(mx);
;   const float mn = fmaxf(m, mx);
;   const float alpha = fexp2(m - mn);
;   const bool rowok = (MODE == 1) ? (vm != 0u) : true;
;   const float mu = (rowok && mn > -1e29f) ? mn : 1e30f;
;   float rs = 0.f;
; #pragma unroll
;   for (int kb = 0; kb < 2; ++kb)
; #pragma unroll
;     for (int i = 0; i < 16; ++i) {
;       const float pv = fexp2(__builtin_fmaf(s[kb][i], SCL2, -mu));
;       s[kb][i] = pv;
;       rs += pv;
;     }
;   rs = xsum32(rs);
;   l = l * alpha + rs;
;   if (__ballot(mn > m) != 0ull) {
; #pragma unroll
;     for (int db = 0; db < 2; ++db)
; #pragma unroll
;       for (int i = 0; i < 16; ++i) o[db][i] *= alpha;
;   }
;   m = mn;
	v_cmp_ne_u32_e32 vcc, 0, v89
	s_nop 1
	v_cndmask_b32_e32 v89, v160, v39, vcc
	v_cmp_ne_u32_e32 vcc, 0, v90
	v_max3_f32 v51, v51, v88, v89
	s_nop 0
	v_cndmask_b32_e32 v90, v160, v40, vcc
	v_cmp_ne_u32_e32 vcc, 0, v91
	s_nop 1
	v_cndmask_b32_e32 v91, v160, v41, vcc
	v_cmp_ne_u32_e32 vcc, 0, v92
	v_max3_f32 v51, v51, v90, v91
	s_nop 0
	v_cndmask_b32_e32 v92, v160, v42, vcc
	v_cmp_ne_u32_e32 vcc, 0, v93
	s_nop 1
	v_cndmask_b32_e32 v93, v160, v43, vcc
	v_cmp_ne_u32_e32 vcc, 0, v94
	v_max3_f32 v51, v51, v92, v93
	s_nop 0
	v_cndmask_b32_e32 v94, v160, v44, vcc
	v_cmp_ne_u32_e32 vcc, 0, v95
	s_nop 1
	v_cndmask_b32_e32 v95, v160, v45, vcc
	v_cmp_ne_u32_e32 vcc, 0, v134
	v_max3_f32 v51, v51, v94, v95
	s_nop 0
	v_cndmask_b32_e32 v134, v160, v46, vcc
	v_cmp_gt_i32_e32 vcc, 0, v48
	s_nop 1
	v_cndmask_b32_e32 v165, v160, v47, vcc
	v_max3_f32 v48, v51, v134, v165
	v_mul_f32_e32 v48, 0x3e38aa3b, v48
	v_mov_b32_e32 v51, v48
	s_nop 1
	v_permlane32_swap_b32_e32 v48, v51
	v_max3_f32 v162, v166, v48, v51
	v_cmp_lt_f32_e32 vcc, s36, v162
	v_sub_f32_e32 v168, v166, v162
	s_nop 0
	v_cndmask_b32_e64 v169, v160, -v162, vcc
	v_fmamk_f32 v48, v49, 0x3e38aa3b, v169
	v_exp_f32_e32 v48, v48
	v_fmamk_f32 v49, v50, 0x3e38aa3b, v169
	v_exp_f32_e32 v49, v49
	v_fmamk_f32 v50, v52, 0x3e38aa3b, v169
	v_exp_f32_e32 v50, v50
	v_fmamk_f32 v51, v53, 0x3e38aa3b, v169
	v_exp_f32_e32 v51, v51
	v_add_f32_e32 v52, 0, v48
	v_add_f32_e32 v52, v49, v52
	v_add_f32_e32 v52, v50, v52
	v_add_f32_e32 v170, v51, v52
	v_fmamk_f32 v52, v54, 0x3e38aa3b, v169
	v_exp_f32_e32 v52, v52
	v_fmamk_f32 v53, v55, 0x3e38aa3b, v169
	v_exp_f32_e32 v53, v53
	v_fmamk_f32 v54, v56, 0x3e38aa3b, v169
	v_exp_f32_e32 v54, v54
	v_fmamk_f32 v55, v57, 0x3e38aa3b, v169
	v_exp_f32_e32 v55, v55
	v_add_f32_e32 v56, v52, v170
	v_add_f32_e32 v56, v53, v56
	v_add_f32_e32 v56, v54, v56
	v_add_f32_e32 v170, v55, v56
	v_fmamk_f32 v56, v58, 0x3e38aa3b, v169
	v_exp_f32_e32 v56, v56
	v_fmamk_f32 v57, v59, 0x3e38aa3b, v169
	v_exp_f32_e32 v57, v57
	v_fmamk_f32 v58, v60, 0x3e38aa3b, v169
	v_exp_f32_e32 v58, v58
	v_fmamk_f32 v59, v61, 0x3e38aa3b, v169
	v_exp_f32_e32 v59, v59
	v_add_f32_e32 v60, v56, v170
	v_add_f32_e32 v60, v57, v60
	v_add_f32_e32 v60, v58, v60
	v_add_f32_e32 v170, v59, v60
	v_fmamk_f32 v60, v62, 0x3e38aa3b, v169
	v_exp_f32_e32 v60, v60
	v_fmamk_f32 v61, v63, 0x3e38aa3b, v169
	v_exp_f32_e32 v61, v61
	v_fmamk_f32 v62, v80, 0x3e38aa3b, v169
	v_exp_f32_e32 v62, v62
	v_fmamk_f32 v63, v81, 0x3e38aa3b, v169
	v_exp_f32_e32 v63, v63
	v_add_f32_e32 v80, v60, v170
	v_add_f32_e32 v80, v61, v80
	v_add_f32_e32 v80, v62, v80
	v_add_f32_e32 v170, v63, v80
	v_fmamk_f32 v80, v82, 0x3e38aa3b, v169
	v_exp_f32_e32 v80, v80
	v_fmamk_f32 v81, v83, 0x3e38aa3b, v169
	v_exp_f32_e32 v81, v81
	v_fmamk_f32 v82, v84, 0x3e38aa3b, v169
	v_exp_f32_e32 v82, v82
	v_fmamk_f32 v83, v85, 0x3e38aa3b, v169
	v_exp_f32_e32 v83, v83
	v_add_f32_e32 v84, v80, v170
	v_add_f32_e32 v84, v81, v84
	v_add_f32_e32 v84, v82, v84
	v_add_f32_e32 v170, v83, v84
	v_fmamk_f32 v84, v86, 0x3e38aa3b, v169
	v_exp_f32_e32 v84, v84
	v_fmamk_f32 v85, v87, 0x3e38aa3b, v169
	v_exp_f32_e32 v85, v85
	v_fmamk_f32 v86, v88, 0x3e38aa3b, v169
	v_exp_f32_e32 v86, v86
	v_fmamk_f32 v87, v89, 0x3e38aa3b, v169
	v_exp_f32_e32 v87, v87
	v_add_f32_e32 v88, v84, v170
	v_add_f32_e32 v88, v85, v88
	v_add_f32_e32 v88, v86, v88
	v_add_f32_e32 v170, v87, v88
	v_fmamk_f32 v88, v90, 0x3e38aa3b, v169
	v_exp_f32_e32 v88, v88
	v_fmamk_f32 v89, v91, 0x3e38aa3b, v169
	v_exp_f32_e32 v89, v89
	v_fmamk_f32 v90, v92, 0x3e38aa3b, v169
	v_exp_f32_e32 v90, v90
	v_fmamk_f32 v91, v93, 0x3e38aa3b, v169
	v_exp_f32_e32 v91, v91
	v_add_f32_e32 v92, v88, v170
	v_add_f32_e32 v92, v89, v92
	v_add_f32_e32 v92, v90, v92
	v_add_f32_e32 v170, v91, v92
	v_fmamk_f32 v92, v94, 0x3e38aa3b, v169
	v_exp_f32_e32 v92, v92
	v_fmamk_f32 v93, v95, 0x3e38aa3b, v169
	v_exp_f32_e32 v93, v93
	v_fmamk_f32 v94, v134, 0x3e38aa3b, v169
	v_exp_f32_e32 v94, v94
	v_fmac_f32_e32 v169, 0x3e38aa3b, v165
	v_exp_f32_e32 v95, v169
	v_add_f32_e32 v134, v92, v170
	v_add_f32_e32 v134, v93, v134
	v_add_f32_e32 v134, v94, v134
	v_add_f32_e32 v165, v95, v134
	v_exp_f32_e32 v134, v168
	v_mov_b32_e32 v168, v165
	s_nop 1
	v_permlane32_swap_b32_e32 v165, v168
	v_cmp_gt_f32_e32 vcc, v162, v166
	v_add_f32_e32 v165, v165, v168
	s_cmp_lg_u64 vcc, 0
	v_fmac_f32_e32 v165, v167, v134
	s_cselect_b64 s[12:13], -1, 0
	s_cbranch_execnz .LBB0_800

; #define MFMA32(a, b, c) __builtin_amdgcn_mfma_f32_32x32x16_bf16((a), (b), (c), 0, 0, 0)
; DI void pv_tile(const u16* Vs, const f32x16* s, f32x16* o, int rl, int hh) {
; #pragma unroll
;   for (int kk = 0; kk < 4; ++kk) {
;     const int kb = kk >> 1, i0 = 8 * (kk & 1);
;     bf16x8 pf = pack8(s[kb][i0], s[kb][i0 + 1], s[kb][i0 + 2], s[kb][i0 + 3], s[kb][i0 + 4], s[kb][i0 + 5], s[kb][i0 + 6], s[kb][i0 + 7]);
; #pragma unroll
;     for (int db = 0; db < 2; ++db) {
;       const u16* vp = Vs + (db * 32 + rl) * KVS + kk * 16 + hh * 4;
;       s16x4 lo = *(const s16x4*)vp, hi = *(const s16x4*)(vp + 8);
;       bf16x8 a = __builtin_shufflevector(lo, hi, 0, 1, 2, 3, 4, 5, 6, 7);
;       o[db] = MFMA32(a, pf, o[db]);
;     }
;   }
; }
.LBB0_804:
	s_nop 0
	v_lshlrev_b32_e32 v36, 1, v129
	v_add3_u32 v40, s28, v125, v36
	s_nop 2
	v_add_u32_e32 v41, 0x2000, v40
	v_add_u32_e32 v40, 0x3000, v40
	ds_read2_b64 v[64:67], v41 offset0:128 offset1:130
	ds_read2_b64 v[68:71], v40 offset0:192 offset1:194
	ds_read2_b64 v[72:75], v41 offset0:132 offset1:134
	ds_read2_b64 v[76:79], v40 offset0:196 offset1:198
	ds_read2_b64 v[36:39], v41 offset0:136 offset1:138
	ds_read2_b64 v[44:47], v40 offset0:200 offset1:202
	v_cvt_pk_bf16_f32 v32, v48, v49
	v_cvt_pk_bf16_f32 v33, v50, v51
	v_cvt_pk_bf16_f32 v34, v52, v53
	v_cvt_pk_bf16_f32 v35, v54, v55
	s_nop 1
	ds_read2_b64 v[48:51], v41 offset0:140 offset1:142
	ds_read2_b64 v[52:55], v40 offset0:204 offset1:206
	s_waitcnt lgkmcnt(7)
	v_mfma_f32_32x32x16_bf16 v[16:31], v[64:67], v[32:35], v[16:31]
	s_waitcnt lgkmcnt(6)
	v_mfma_f32_32x32x16_bf16 v[0:15], v[68:71], v[32:35], v[0:15]
	v_cvt_pk_bf16_f32 v32, v56, v57
	v_cvt_pk_bf16_f32 v33, v58, v59
	v_cvt_pk_bf16_f32 v34, v60, v61
	v_cvt_pk_bf16_f32 v35, v62, v63
	s_nop 1
	s_waitcnt lgkmcnt(5)
	v_mfma_f32_32x32x16_bf16 v[16:31], v[72:75], v[32:35], v[16:31]
	s_waitcnt lgkmcnt(4)
	v_mfma_f32_32x32x16_bf16 v[0:15], v[76:79], v[32:35], v[0:15]
	v_cvt_pk_bf16_f32 v32, v80, v81
	v_cvt_pk_bf16_f32 v33, v82, v83
	v_cvt_pk_bf16_f32 v34, v84, v85
	v_cvt_pk_bf16_f32 v35, v86, v87
	s_nop 1
	s_waitcnt lgkmcnt(3)
	v_mfma_f32_32x32x16_bf16 v[16:31], v[36:39], v[32:35], v[16:31]
	s_waitcnt lgkmcnt(2)
	v_mfma_f32_32x32x16_bf16 v[0:15], v[44:47], v[32:35], v[0:15]
	v_cvt_pk_bf16_f32 v32, v88, v89
	v_cvt_pk_bf16_f32 v33, v90, v91
	v_cvt_pk_bf16_f32 v34, v92, v93
	v_cvt_pk_bf16_f32 v35, v94, v95
	s_nop 1
	s_waitcnt lgkmcnt(1)
	v_mfma_f32_32x32x16_bf16 v[16:31], v[48:51], v[32:35], v[16:31]
	s_waitcnt lgkmcnt(0)
	v_mfma_f32_32x32x16_bf16 v[0:15], v[52:55], v[32:35], v[0:15]
	s_branch .LBB0_806

; #define MFMA32(a, b, c) __builtin_amdgcn_mfma_f32_32x32x16_bf16((a), (b), (c), 0, 0, 0)
; DI void qk_tile(const u16* Ks, const bf16x8* qf, f32x16* s, int rl, int hh) {
; #pragma unroll
;   for (int kb = 0; kb < 2; ++kb) {
; #pragma unroll
;     for (int i = 0; i < 16; ++i) s[kb][i] = 0.f;
; #pragma unroll
;     for (int ks = 0; ks < 4; ++ks) {
;       bf16x8 a = *(const bf16x8*)(Ks + (kb * 32 + rl) * KVS + ks * 16 + hh * 8);
;       s[kb] = MFMA32(a, qf[ks], s[kb]);
;     }
;   }
; }
; DI void nsa_item(int ws, PP p, char* shm, int item) {
;     ...
;     auto body1 = [&](int i, const u16* Ks, const u16* Vs) {
;       const uint32_t vm = range_mask(i * 64, 0, cmax, hh);
;       f32x16 s[2];
;       qk_tile(Ks, qn, s, rl, hh);
;       float mx = -1e30f;
; #pragma unroll
;       for (int kb = 0; kb < 2; ++kb)
; #pragma unroll
;         for (int ii = 0; ii < 16; ++ii) {
;           float v = s[kb][ii] * SCL2;
;           v = ((vm >> (kb * 16 + ii)) & 1u) ? v : -1e30f;
;           s[kb][ii] = v;
;           mx = fmaxf(mx, v);
;         }
;       mx = xmax32(mx);
;       const float mn = fmaxf(m, mx);
.LBB0_1599:
	s_or_b64 exec, exec, s[10:11]
	s_and_b32 s79, s78, 1
	s_mul_i32 s10, s79, 0x4800
	v_add_u32_e32 v60, s10, v52
	ds_read_b128 v[126:129], v60
	ds_read_b128 v[130:133], v60 offset:32
	ds_read_b128 v[134:137], v60 offset:64
	ds_read_b128 v[138:141], v60 offset:96
	ds_read_b128 v[148:151], v60 offset:4608
	ds_read_b128 v[152:155], v60 offset:4640
	ds_read_b128 v[156:159], v60 offset:4672
	ds_read_b128 v[160:163], v60 offset:4704
	v_cmp_lt_i32_e64 s[20:21], -1, v55
	s_waitcnt lgkmcnt(7)
	v_mfma_f32_32x32x16_bf16 v[18:33], v[126:129], v[80:83], 0
	s_waitcnt lgkmcnt(6)
	v_mfma_f32_32x32x16_bf16 v[18:33], v[130:133], v[176:179], v[18:33]
	s_waitcnt lgkmcnt(5)
	v_mfma_f32_32x32x16_bf16 v[18:33], v[134:137], v[180:183], v[18:33]
	s_waitcnt lgkmcnt(4)
	v_mfma_f32_32x32x16_bf16 v[18:33], v[138:141], v[184:187], v[18:33]
	s_waitcnt lgkmcnt(3)
	v_mfma_f32_32x32x16_bf16 v[2:17], v[148:151], v[80:83], 0
	s_waitcnt lgkmcnt(2)
	v_mfma_f32_32x32x16_bf16 v[2:17], v[152:155], v[176:179], v[2:17]
	s_waitcnt lgkmcnt(1)
	v_mfma_f32_32x32x16_bf16 v[2:17], v[156:159], v[180:183], v[2:17]
	s_waitcnt lgkmcnt(0)
	v_mfma_f32_32x32x16_bf16 v[2:17], v[160:163], v[184:187], v[2:17]
	s_nop 1
	v_mul_f32_e32 v56, 0x3e38aa3b, v18
	v_and_b32_e32 v57, 1, v55
	v_and_b32_e32 v58, 2, v55
	v_cmp_eq_u32_e32 vcc, 0, v57
	v_max_f32_e32 v56, 0xf149f2ca, v56
	v_mul_f32_e32 v57, 0x3e38aa3b, v19
	v_cmp_eq_u32_e64 s[10:11], 0, v58
	v_cndmask_b32_e32 v56, v56, v204, vcc
	v_and_b32_e32 v58, 4, v55
	v_cndmask_b32_e64 v57, v57, v204, s[10:11]
	v_and_b32_e32 v59, 8, v55
	v_max_f32_e32 v56, v56, v57
	v_mul_f32_e32 v57, 0x3e38aa3b, v20
	v_cmp_eq_u32_e64 s[14:15], 0, v58
	v_mul_f32_e32 v58, 0x3e38aa3b, v21
	v_cmp_eq_u32_e64 s[12:13], 0, v59
	v_cndmask_b32_e64 v57, v57, v204, s[14:15]
	v_and_b32_e32 v59, 32, v55
	v_cndmask_b32_e64 v58, v58, v204, s[12:13]
	v_max3_f32 v56, v56, v57, v58
	v_and_b32_e32 v58, 16, v55
	v_mul_f32_e32 v57, 0x3e38aa3b, v22
	v_cmp_eq_u32_e64 s[16:17], 0, v58
	v_mul_f32_e32 v58, 0x3e38aa3b, v23
	v_cmp_eq_u32_e64 s[18:19], 0, v59
	v_cndmask_b32_e64 v57, v57, v204, s[16:17]
	v_and_b32_e32 v59, 0x80, v55
	v_cndmask_b32_e64 v58, v58, v204, s[18:19]
	v_max3_f32 v56, v56, v57, v58
	v_and_b32_e32 v58, 64, v55
	v_mul_f32_e32 v57, 0x3e38aa3b, v24
	v_cmp_eq_u32_e64 s[48:49], 0, v58
	v_mul_f32_e32 v58, 0x3e38aa3b, v25
	v_cmp_eq_u32_e64 s[66:67], 0, v59
	v_cndmask_b32_e64 v57, v57, v204, s[48:49]
	v_and_b32_e32 v59, 0x200, v55
	v_cndmask_b32_e64 v58, v58, v204, s[66:67]
	v_max3_f32 v56, v56, v57, v58
	v_and_b32_e32 v58, 0x100, v55
	v_mul_f32_e32 v57, 0x3e38aa3b, v26
	v_cmp_eq_u32_e64 s[68:69], 0, v58
	v_mul_f32_e32 v58, 0x3e38aa3b, v27
	v_cmp_eq_u32_e64 s[70:71], 0, v59
	v_cndmask_b32_e64 v57, v57, v204, s[68:69]
	v_and_b32_e32 v59, 0x800, v55
	v_cndmask_b32_e64 v58, v58, v204, s[70:71]
	v_max3_f32 v56, v56, v57, v58
	v_and_b32_e32 v58, 0x400, v55
	v_mul_f32_e32 v57, 0x3e38aa3b, v28
	v_cmp_eq_u32_e64 s[72:73], 0, v58
	v_mul_f32_e32 v58, 0x3e38aa3b, v29
	v_cmp_eq_u32_e64 s[60:61], 0, v59
	v_cndmask_b32_e64 v57, v57, v204, s[72:73]
	v_and_b32_e32 v59, 0x2000, v55
	v_cndmask_b32_e64 v58, v58, v204, s[60:61]
	v_max3_f32 v56, v56, v57, v58
	v_and_b32_e32 v58, 0x1000, v55
	v_mul_f32_e32 v57, 0x3e38aa3b, v30
	v_cmp_eq_u32_e64 s[64:65], 0, v58
	v_mul_f32_e32 v58, 0x3e38aa3b, v31
	v_cmp_eq_u32_e64 s[62:63], 0, v59
	v_cndmask_b32_e64 v57, v57, v204, s[64:65]
	v_and_b32_e32 v59, 0x8000, v55
	v_cndmask_b32_e64 v58, v58, v204, s[62:63]
	v_max3_f32 v56, v56, v57, v58
	v_and_b32_e32 v58, 0x4000, v55
	v_mul_f32_e32 v57, 0x3e38aa3b, v32
	v_cmp_eq_u32_e64 s[58:59], 0, v58
	v_mul_f32_e32 v58, 0x3e38aa3b, v33
	v_cmp_eq_u32_e64 s[52:53], 0, v59
	v_cndmask_b32_e64 v57, v57, v204, s[58:59]
	v_and_b32_e32 v59, 0x20000, v55
	v_cndmask_b32_e64 v58, v58, v204, s[52:53]
	v_max3_f32 v56, v56, v57, v58
	v_and_b32_e32 v58, 0x10000, v55
	v_mul_f32_e32 v57, 0x3e38aa3b, v2
	v_cmp_eq_u32_e64 s[56:57], 0, v58
	v_mul_f32_e32 v58, 0x3e38aa3b, v3
	v_cmp_eq_u32_e64 s[54:55], 0, v59
	v_cndmask_b32_e64 v57, v57, v204, s[56:57]
	v_and_b32_e32 v59, 0x80000, v55
	v_cndmask_b32_e64 v58, v58, v204, s[54:55]
	v_max3_f32 v56, v56, v57, v58
	v_and_b32_e32 v58, 0x40000, v55
	v_mul_f32_e32 v57, 0x3e38aa3b, v4
	v_cmp_eq_u32_e64 s[50:51], 0, v58
	v_mul_f32_e32 v58, 0x3e38aa3b, v5
	v_cmp_eq_u32_e64 s[42:43], 0, v59
	v_cndmask_b32_e64 v57, v57, v204, s[50:51]
	v_and_b32_e32 v59, 0x200000, v55
	v_cndmask_b32_e64 v58, v58, v204, s[42:43]
	v_max3_f32 v56, v56, v57, v58
	v_and_b32_e32 v58, 0x100000, v55
	v_mul_f32_e32 v57, 0x3e38aa3b, v6
	v_cmp_eq_u32_e64 s[46:47], 0, v58
	v_mul_f32_e32 v58, 0x3e38aa3b, v7
	v_cmp_eq_u32_e64 s[44:45], 0, v59
	v_cndmask_b32_e64 v57, v57, v204, s[46:47]
	v_and_b32_e32 v59, 0x800000, v55
	v_cndmask_b32_e64 v58, v58, v204, s[44:45]
	v_max3_f32 v56, v56, v57, v58
	v_and_b32_e32 v58, 0x400000, v55
	v_mul_f32_e32 v57, 0x3e38aa3b, v8
	v_cmp_eq_u32_e64 s[40:41], 0, v58
	v_mul_f32_e32 v58, 0x3e38aa3b, v9
	v_cmp_eq_u32_e64 s[34:35], 0, v59
	v_cndmask_b32_e64 v57, v57, v204, s[40:41]
	v_and_b32_e32 v59, 0x2000000, v55
	v_cndmask_b32_e64 v58, v58, v204, s[34:35]
	v_max3_f32 v56, v56, v57, v58
	v_and_b32_e32 v58, 0x1000000, v55
	v_mul_f32_e32 v57, 0x3e38aa3b, v10
	v_cmp_eq_u32_e64 s[38:39], 0, v58
	v_mul_f32_e32 v58, 0x3e38aa3b, v11
	v_cmp_eq_u32_e64 s[36:37], 0, v59
	v_cndmask_b32_e64 v57, v57, v204, s[38:39]
; DI float fexp2(float x) { return __builtin_amdgcn_exp2f(x); }
; template <class TF, class BODY>
; DI void kv_loop(u16* kvb, int ntiles, int tid, TF tf, BODY body) {
;     ...
;     if (i + 1 < ntiles) kv_write(r, kvb + (cur ^ 1) * 2 * KVT, kvb + (cur ^ 1) * 2 * KVT + KVT, tid);
; DI void nsa_item(int ws, PP p, char* shm, int item) {
;     ...
;       mx = xmax32(mx);
;       const float mn = fmaxf(m, mx);
;       float rs = 0.f;
; #pragma unroll
;       for (int kb = 0; kb < 2; ++kb)
; #pragma unroll
;         for (int ii = 0; ii < 16; ++ii) rs += ((vm >> (kb * 16 + ii)) & 1u) ? fexp2(s[kb][ii] - mn) : 0.f;
;       rs = xsum32(rs);
;       l = l * fexp2(m - mn) + rs;
;       m = mn;
;     };
	v_and_b32_e32 v59, 0x8000000, v55
	v_cndmask_b32_e64 v58, v58, v204, s[36:37]
	v_max3_f32 v56, v56, v57, v58
	v_and_b32_e32 v58, 0x4000000, v55
	v_mul_f32_e32 v57, 0x3e38aa3b, v12
	v_cmp_eq_u32_e64 s[30:31], 0, v58
	v_mul_f32_e32 v58, 0x3e38aa3b, v13
	v_cmp_eq_u32_e64 s[24:25], 0, v59
	v_cndmask_b32_e64 v57, v57, v204, s[30:31]
	v_and_b32_e32 v59, 0x20000000, v55
	v_cndmask_b32_e64 v58, v58, v204, s[24:25]
	v_max3_f32 v56, v56, v57, v58
	v_and_b32_e32 v58, 0x10000000, v55
	v_mul_f32_e32 v57, 0x3e38aa3b, v14
	v_cmp_eq_u32_e64 s[28:29], 0, v58
	v_mul_f32_e32 v58, 0x3e38aa3b, v15
	v_cmp_eq_u32_e64 s[26:27], 0, v59
	v_cndmask_b32_e64 v57, v57, v204, s[28:29]
	s_nop 0
	v_cndmask_b32_e64 v58, v58, v204, s[26:27]
	v_max3_f32 v56, v56, v57, v58
	v_and_b32_e32 v58, 2.0, v55
	v_mul_f32_e32 v57, 0x3e38aa3b, v16
	v_cmp_eq_u32_e64 s[22:23], 0, v58
	v_mul_f32_e32 v58, 0x3e38aa3b, v17
	v_cndmask_b32_e64 v55, v58, v204, s[20:21]
	v_cndmask_b32_e64 v57, v57, v204, s[22:23]
	v_max3_f32 v55, v56, v57, v55
	v_mov_b32_e32 v56, v55
	s_nop 1
	v_permlane32_swap_b32_e32 v55, v56
	v_max3_f32 v124, v54, v55, v56
	v_fma_f32 v18, v18, s9, -v124
	v_exp_f32_e32 v18, v18
	v_fma_f32 v19, v19, s9, -v124
	v_exp_f32_e32 v19, v19
	v_fma_f32 v20, v20, s9, -v124
	v_exp_f32_e32 v20, v20
	v_fma_f32 v21, v21, s9, -v124
	v_exp_f32_e32 v21, v21
	v_fma_f32 v22, v22, s9, -v124
	v_add_f32_e32 v18, 0, v18
	v_exp_f32_e32 v22, v22
	v_fma_f32 v23, v23, s9, -v124
	v_cndmask_b32_e64 v18, v18, 0, vcc
	v_cndmask_b32_e64 v19, v19, 0, s[10:11]
	v_exp_f32_e32 v23, v23
	v_fma_f32 v24, v24, s9, -v124
	v_cndmask_b32_e64 v20, v20, 0, s[14:15]
	v_exp_f32_e32 v24, v24
	v_fma_f32 v25, v25, s9, -v124
	v_add_f32_e32 v18, v19, v18
	v_cndmask_b32_e64 v21, v21, 0, s[12:13]
	v_exp_f32_e32 v25, v25
	v_fma_f32 v26, v26, s9, -v124
	v_add_f32_e32 v18, v20, v18
	v_cndmask_b32_e64 v22, v22, 0, s[16:17]
	v_exp_f32_e32 v26, v26
	v_fma_f32 v27, v27, s9, -v124
	v_add_f32_e32 v18, v21, v18
	v_cndmask_b32_e64 v23, v23, 0, s[18:19]
	v_exp_f32_e32 v27, v27
	v_fma_f32 v28, v28, s9, -v124
	v_add_f32_e32 v18, v22, v18
	v_cndmask_b32_e64 v24, v24, 0, s[48:49]
	v_exp_f32_e32 v28, v28
	v_fma_f32 v29, v29, s9, -v124
	v_add_f32_e32 v18, v23, v18
	v_cndmask_b32_e64 v25, v25, 0, s[66:67]
	v_exp_f32_e32 v29, v29
	v_fma_f32 v30, v30, s9, -v124
	v_add_f32_e32 v18, v24, v18
	v_cndmask_b32_e64 v26, v26, 0, s[68:69]
	v_exp_f32_e32 v30, v30
	v_fma_f32 v31, v31, s9, -v124
	v_add_f32_e32 v18, v25, v18
	v_cndmask_b32_e64 v27, v27, 0, s[70:71]
	v_exp_f32_e32 v31, v31
	v_fma_f32 v32, v32, s9, -v124
	v_add_f32_e32 v18, v26, v18
	v_cndmask_b32_e64 v28, v28, 0, s[72:73]
	v_exp_f32_e32 v32, v32
	v_fma_f32 v33, v33, s9, -v124
	v_add_f32_e32 v18, v27, v18
	v_cndmask_b32_e64 v29, v29, 0, s[60:61]
	v_exp_f32_e32 v33, v33
	v_fma_f32 v2, v2, s9, -v124
	v_add_f32_e32 v18, v28, v18
	v_cndmask_b32_e64 v30, v30, 0, s[64:65]
	v_exp_f32_e32 v2, v2
	v_fma_f32 v3, v3, s9, -v124
	v_add_f32_e32 v18, v29, v18
	v_cndmask_b32_e64 v31, v31, 0, s[62:63]
	v_exp_f32_e32 v3, v3
	v_fma_f32 v4, v4, s9, -v124
	v_add_f32_e32 v18, v30, v18
	v_cndmask_b32_e64 v32, v32, 0, s[58:59]
	v_exp_f32_e32 v4, v4
	v_fma_f32 v5, v5, s9, -v124
	v_add_f32_e32 v18, v31, v18
	v_cndmask_b32_e64 v33, v33, 0, s[52:53]
	v_exp_f32_e32 v5, v5
	v_fma_f32 v6, v6, s9, -v124
	v_add_f32_e32 v18, v32, v18
	v_cndmask_b32_e64 v2, v2, 0, s[56:57]
	v_exp_f32_e32 v6, v6
	v_fma_f32 v7, v7, s9, -v124
	v_add_f32_e32 v18, v33, v18
	v_cndmask_b32_e64 v3, v3, 0, s[54:55]
	v_exp_f32_e32 v7, v7
	v_fma_f32 v8, v8, s9, -v124
	v_add_f32_e32 v2, v2, v18
	v_cndmask_b32_e64 v4, v4, 0, s[50:51]
	v_exp_f32_e32 v8, v8
	v_fma_f32 v9, v9, s9, -v124
	v_add_f32_e32 v2, v3, v2
	v_cndmask_b32_e64 v5, v5, 0, s[42:43]
	v_exp_f32_e32 v9, v9
	v_fma_f32 v10, v10, s9, -v124
	v_add_f32_e32 v2, v4, v2
	v_cndmask_b32_e64 v6, v6, 0, s[46:47]
	v_exp_f32_e32 v10, v10
	v_fma_f32 v11, v11, s9, -v124
	v_add_f32_e32 v2, v5, v2
	v_cndmask_b32_e64 v7, v7, 0, s[44:45]
	v_exp_f32_e32 v11, v11
	v_fma_f32 v12, v12, s9, -v124
	v_add_f32_e32 v2, v6, v2
	v_cndmask_b32_e64 v8, v8, 0, s[40:41]
	v_exp_f32_e32 v12, v12
	v_fma_f32 v13, v13, s9, -v124
	v_add_f32_e32 v2, v7, v2
	v_cndmask_b32_e64 v9, v9, 0, s[34:35]
	v_exp_f32_e32 v13, v13
	v_fma_f32 v14, v14, s9, -v124
	v_add_f32_e32 v2, v8, v2
	v_cndmask_b32_e64 v10, v10, 0, s[38:39]
	v_exp_f32_e32 v14, v14
	v_fma_f32 v15, v15, s9, -v124
	v_add_f32_e32 v2, v9, v2
	v_cndmask_b32_e64 v11, v11, 0, s[36:37]
	v_exp_f32_e32 v15, v15
	v_fma_f32 v16, v16, s9, -v124
	v_add_f32_e32 v2, v10, v2
	v_cndmask_b32_e64 v12, v12, 0, s[30:31]
	v_exp_f32_e32 v16, v16
	v_fma_f32 v17, v17, s9, -v124
	v_add_f32_e32 v2, v11, v2
	v_cndmask_b32_e64 v13, v13, 0, s[24:25]
	v_exp_f32_e32 v17, v17
	v_add_f32_e32 v2, v12, v2
	v_cndmask_b32_e64 v14, v14, 0, s[28:29]
	v_add_f32_e32 v2, v13, v2
	v_cndmask_b32_e64 v15, v15, 0, s[26:27]
	v_add_f32_e32 v2, v14, v2
	v_cndmask_b32_e64 v16, v16, 0, s[22:23]
	v_add_f32_e32 v2, v15, v2
	v_cndmask_b32_e64 v17, v17, 0, s[20:21]
	v_add_f32_e32 v2, v16, v2
	v_add_f32_e32 v2, v17, v2
	v_mov_b32_e32 v3, v2
	s_nop 1
	v_permlane32_swap_b32_e32 v2, v3
	s_andn2_b64 vcc, exec, s[92:93]
	s_cbranch_vccnz .LBB0_1601
	s_lshl_b32 s10, s79, 1
	s_xor_b32 s10, s10, 2
	s_mulk_i32 s10, 0x2400
	v_add_u32_e32 v4, s10, v245
	s_waitcnt vmcnt(1)
	ds_write_b128 v4, v[34:37]
	s_waitcnt vmcnt(0)
	ds_write_b128 v4, v[38:41] offset:9216

; DI void nsa_item(int ws, PP p, char* shm, int item) {
;     ...
;     uint32_t pfx = 0;
; #pragma unroll 1
;     for (int b = 31; b >= 0; --b) {
;       const uint32_t cand = pfx | (1u << b);
;       int c = 0;
; #pragma unroll
;       for (int e = 0; e < 8; ++e) c += (key[e] >= cand) ? 1 : 0;
;       c = rowsum(c);
;       if (c >= 16) pfx = cand;
;     }
;     int cgt = 0, teq = 0;
; #pragma unroll
;     for (int e = 0; e < 8; ++e) { cgt += (key[e] > pfx) ? 1 : 0; teq += (key[e] == pfx) ? 1 : 0; }
;     cgt = rowsum(cgt);
;     int tin = teq;
;     tin += __builtin_amdgcn_update_dpp(0, tin, 0x111, 0xF, 0xF, true);
;     tin += __builtin_amdgcn_update_dpp(0, tin, 0x112, 0xF, 0xF, true);
;     tin += __builtin_amdgcn_update_dpp(0, tin, 0x114, 0xF, 0xF, true);
;     tin += __builtin_amdgcn_update_dpp(0, tin, 0x118, 0xF, 0xF, true);
;     int run = cgt + tin - teq;
;     uint32_t bits = 0;
; #pragma unroll
;     for (int e = 0; e < 8; ++e) {
;       const bool eq = key[e] == pfx;
;       const bool sel = (key[e] > pfx) || (eq && run < 16);
;       run += eq ? 1 : 0;
;       bits |= (sel && (jg * 8 + e) <= blk) ? (1u << e) : 0u;
;     }
;     selb[tk * 16 + jg] = (unsigned char)bits;
;     __syncthreads();
.LBB0_1629:
	v_lshl_or_b32 v13, 1, s4, v12
	v_cmp_ge_u32_e32 vcc, v3, v13
	s_add_i32 s4, s4, -1
	s_cmp_eq_u32 s4, -1
	v_cndmask_b32_e64 v14, 0, 1, vcc
	v_cmp_ge_u32_e32 vcc, v2, v13
	s_nop 1
	v_addc_co_u32_e32 v14, vcc, 0, v14, vcc
	v_cmp_ge_u32_e32 vcc, v4, v13
	s_nop 1
	v_cndmask_b32_e64 v15, 0, 1, vcc
	v_cmp_ge_u32_e32 vcc, v5, v13
	s_nop 1
	v_addc_co_u32_e32 v14, vcc, v14, v15, vcc
	v_cmp_ge_u32_e32 vcc, v6, v13
	s_nop 1
	v_cndmask_b32_e64 v15, 0, 1, vcc
	v_cmp_ge_u32_e32 vcc, v7, v13
	s_nop 1
	v_addc_co_u32_e32 v14, vcc, v14, v15, vcc
	v_cmp_ge_u32_e32 vcc, v8, v13
	s_nop 1
	v_cndmask_b32_e64 v15, 0, 1, vcc
	v_cmp_ge_u32_e32 vcc, v9, v13
	s_nop 1
	v_addc_co_u32_e32 v14, vcc, v14, v15, vcc
	s_nop 1
	v_add_u32_dpp v14, v14, v14 row_ror:8 row_mask:0xf bank_mask:0xf bound_ctrl:1
	s_nop 1
	v_add_u32_dpp v14, v14, v14 row_ror:4 row_mask:0xf bank_mask:0xf bound_ctrl:1
	s_nop 1
	v_add_u32_dpp v14, v14, v14 row_ror:2 row_mask:0xf bank_mask:0xf bound_ctrl:1
	s_nop 1
	v_add_u32_dpp v14, v14, v14 row_ror:1 row_mask:0xf bank_mask:0xf bound_ctrl:1
	v_cmp_lt_i32_e32 vcc, 15, v14
	s_nop 1
	v_cndmask_b32_e32 v12, v12, v13, vcc
	s_cbranch_scc0 .LBB0_1629
	v_cmp_gt_u32_e64 s[10:11], v3, v12
	v_cmp_gt_u32_e64 s[12:13], v2, v12
	v_cmp_eq_u32_e32 vcc, v2, v12
	v_cndmask_b32_e64 v14, 0, 1, s[10:11]
	v_addc_co_u32_e64 v2, s[14:15], 0, v14, s[12:13]
	v_cmp_eq_u32_e64 s[14:15], v3, v12
	v_cmp_gt_u32_e64 s[20:21], v5, v12
	v_cmp_eq_u32_e64 s[18:19], v4, v12
	v_cndmask_b32_e64 v3, 0, 1, s[14:15]
	v_addc_co_u32_e64 v14, s[16:17], 0, v3, vcc
	v_cmp_gt_u32_e64 s[16:17], v4, v12
	v_cndmask_b32_e64 v4, 0, 1, s[18:19]
	v_cmp_gt_u32_e64 s[28:29], v7, v12
	v_cndmask_b32_e64 v15, 0, 1, s[16:17]
	v_addc_co_u32_e64 v2, s[22:23], v2, v15, s[20:21]
	v_cmp_eq_u32_e64 s[22:23], v5, v12
	v_cmp_eq_u32_e64 s[26:27], v6, v12
	v_cmp_gt_u32_e64 s[38:39], v9, v12
	v_addc_co_u32_e64 v14, s[24:25], v14, v4, s[22:23]
	v_cmp_gt_u32_e64 s[24:25], v6, v12
	v_cndmask_b32_e64 v6, 0, 1, s[26:27]
	v_cmp_eq_u32_e64 s[36:37], v8, v12
	v_cndmask_b32_e64 v15, 0, 1, s[24:25]
	v_addc_co_u32_e64 v2, s[30:31], v2, v15, s[28:29]
	v_cmp_eq_u32_e64 s[30:31], v7, v12
	v_cndmask_b32_e64 v13, 0, 1, vcc
	v_cndmask_b32_e64 v5, 0, 1, s[22:23]
	v_addc_co_u32_e64 v14, s[34:35], v14, v6, s[30:31]
	v_cmp_gt_u32_e64 s[34:35], v8, v12
	v_cndmask_b32_e64 v8, 0, 1, s[36:37]
	v_cndmask_b32_e64 v7, 0, 1, s[30:31]
	v_cndmask_b32_e64 v15, 0, 1, s[34:35]
	v_addc_co_u32_e64 v2, s[40:41], v2, v15, s[38:39]
	v_cmp_eq_u32_e64 s[40:41], v9, v12
	s_nop 0
	v_add_u32_dpp v2, v2, v2 row_ror:8 row_mask:0xf bank_mask:0xf bound_ctrl:1
	v_addc_co_u32_e64 v8, s[42:43], v14, v8, s[40:41]
	s_nop 0
	v_add_u32_dpp v2, v2, v2 row_ror:4 row_mask:0xf bank_mask:0xf bound_ctrl:1
	v_add_u32_dpp v9, v8, v8 row_shr:1 row_mask:0xf bank_mask:0xf bound_ctrl:1
	s_nop 0
	v_add_u32_dpp v2, v2, v2 row_ror:2 row_mask:0xf bank_mask:0xf bound_ctrl:1
	v_add_u32_dpp v9, v9, v9 row_shr:2 row_mask:0xf bank_mask:0xf bound_ctrl:1
	s_nop 0
	v_sub_u32_dpp v8, v2, v8 row_ror:1 row_mask:0xf bank_mask:0xf bound_ctrl:1
	v_add_u32_dpp v9, v9, v9 row_shr:4 row_mask:0xf bank_mask:0xf bound_ctrl:1
	v_add_u32_e32 v2, v8, v2
	v_sub_u32_e32 v8, v11, v10
	v_mov_b32_dpp v12, v9 row_shr:8 row_mask:0xf bank_mask:0xf bound_ctrl:1
	v_add3_u32 v2, v2, v12, v9
	v_cmp_gt_i32_e64 s[42:43], 16, v2
	s_and_b64 s[4:5], vcc, s[42:43]
	v_addc_co_u32_e32 v9, vcc, 0, v2, vcc
	s_or_b64 s[4:5], s[12:13], s[4:5]
	v_cmp_lt_i32_e32 vcc, -1, v8
	s_and_b64 s[4:5], s[4:5], vcc
	v_cmp_gt_i32_e32 vcc, 16, v9
	v_cndmask_b32_e64 v10, 0, 1, s[4:5]
	s_and_b64 s[4:5], s[14:15], vcc
	v_addc_co_u32_e64 v2, vcc, v2, v13, s[14:15]
	s_or_b64 s[4:5], s[10:11], s[4:5]
	v_cmp_lt_i32_e32 vcc, 0, v8
	s_and_b64 s[4:5], s[4:5], vcc
	v_cmp_gt_i32_e32 vcc, 16, v2
	v_cndmask_b32_e64 v11, 0, 2, s[4:5]
	s_and_b64 s[4:5], s[18:19], vcc
	v_addc_co_u32_e64 v3, vcc, v9, v3, s[18:19]
	v_cmp_gt_i32_e32 vcc, 2, v8
	v_or_b32_e32 v10, v11, v10
	s_nop 0
	v_cndmask_b32_e64 v9, 4, 0, vcc
	s_or_b64 vcc, s[16:17], s[4:5]
	v_cndmask_b32_e32 v9, 0, v9, vcc
	v_cmp_gt_i32_e32 vcc, 16, v3
	s_and_b64 s[4:5], s[22:23], vcc
	v_addc_co_u32_e64 v2, vcc, v2, v4, s[22:23]
	v_cmp_gt_i32_e32 vcc, 3, v8
	s_nop 1
	v_cndmask_b32_e64 v4, 8, 0, vcc
	s_or_b64 vcc, s[20:21], s[4:5]
	v_cndmask_b32_e32 v4, 0, v4, vcc
	v_cmp_gt_i32_e32 vcc, 16, v2
	s_and_b64 s[4:5], s[26:27], vcc
	v_addc_co_u32_e64 v3, vcc, v3, v5, s[26:27]
	v_cmp_gt_i32_e32 vcc, 4, v8
	v_bitop3_b16 v4, v10, v4, v9 bitop3:0xfe
	s_nop 0
	v_cndmask_b32_e64 v5, 16, 0, vcc
	s_or_b64 vcc, s[24:25], s[4:5]
	v_cndmask_b32_e32 v5, 0, v5, vcc
	v_cmp_gt_i32_e32 vcc, 16, v3
	s_and_b64 s[4:5], s[30:31], vcc
	v_addc_co_u32_e64 v2, vcc, v2, v6, s[30:31]
	v_cmp_gt_i32_e32 vcc, 5, v8
	s_nop 1
	v_cndmask_b32_e64 v6, 32, 0, vcc
	s_or_b64 vcc, s[28:29], s[4:5]
	v_cndmask_b32_e32 v6, 0, v6, vcc
	v_cmp_gt_i32_e32 vcc, 16, v2
	s_and_b64 s[4:5], s[36:37], vcc
	v_addc_co_u32_e64 v2, vcc, v3, v7, s[36:37]
	v_cmp_gt_i32_e32 vcc, 6, v8
	v_bitop3_b16 v4, v4, v6, v5 bitop3:0xfe
	s_nop 0
	v_cndmask_b32_e64 v3, 64, 0, vcc
	s_or_b64 vcc, s[34:35], s[4:5]
	v_cndmask_b32_e32 v3, 0, v3, vcc
	v_cmp_gt_i32_e32 vcc, 16, v2
	s_and_b64 s[4:5], s[40:41], vcc
	v_cmp_gt_i32_e32 vcc, 7, v8
	s_nop 1
	v_cndmask_b32_e64 v2, v242, 0, vcc
	s_or_b64 vcc, s[38:39], s[4:5]
	v_cndmask_b32_e32 v2, 0, v2, vcc
	v_bitop3_b16 v2, v4, v2, v3 bitop3:0xfe
	v_add_u32_e32 v3, 0x24000, v101
	v_cmp_gt_i32_e32 vcc, 32, v101
	ds_write_b8 v3, v2
	s_waitcnt lgkmcnt(0)
	s_barrier
; DI void nsa_item(int ws, PP p, char* shm, int item) {
;     ...
;     if (tid < 32) {
;       const uint32_t* w = (const uint32_t*)(selb + tid * 16);
;       atomicOr(&un[0], w[0]); atomicOr(&un[1], w[1]); atomicOr(&un[2], w[2]); atomicOr(&un[3], w[3]);
;     }
	s_and_saveexec_b64 s[10:11], vcc
	s_cbranch_execz .LBB0_1647
	v_lshlrev_b32_e32 v2, 4, v101
	v_add_u32_e32 v3, 0x24000, v2
	ds_read_b32 v3, v3
	s_mov_b64 s[12:13], exec
	s_mov_b32 s4, 0
	s_waitcnt lgkmcnt(0)
	v_or_b32_dpp v3, v3, v3 row_ror:8 row_mask:0xf bank_mask:0xf bound_ctrl:1
	s_nop 1
	v_or_b32_dpp v3, v3, v3 row_ror:4 row_mask:0xf bank_mask:0xf bound_ctrl:1
	s_nop 1
	v_or_b32_dpp v3, v3, v3 row_ror:2 row_mask:0xf bank_mask:0xf bound_ctrl:1
	s_nop 1
	v_or_b32_dpp v3, v3, v3 row_ror:1 row_mask:0xf bank_mask:0xf bound_ctrl:1
	s_nop 1
	v_readlane_b32 s4, v3, 0
	v_readlane_b32 s16, v3, 16
	s_or_b32 s4, s4, s16
	v_mbcnt_lo_u32_b32 v3, exec_lo, 0
	v_mbcnt_hi_u32_b32 v3, exec_hi, v3
	v_cmp_eq_u32_e32 vcc, 0, v3
	s_and_saveexec_b64 s[12:13], vcc
	s_xor_b64 s[12:13], exec, s[12:13]
	v_mov_b32_e32 v3, s4
	ds_or_b32 v228, v3
	s_or_b64 exec, exec, s[12:13]
	v_add_u32_e32 v3, 0x24004, v2
	ds_read_b32 v3, v3
	s_mov_b64 s[12:13], exec
	s_mov_b32 s4, 0
	s_waitcnt lgkmcnt(0)
	v_or_b32_dpp v3, v3, v3 row_ror:8 row_mask:0xf bank_mask:0xf bound_ctrl:1
	s_nop 1
	v_or_b32_dpp v3, v3, v3 row_ror:4 row_mask:0xf bank_mask:0xf bound_ctrl:1
	s_nop 1
	v_or_b32_dpp v3, v3, v3 row_ror:2 row_mask:0xf bank_mask:0xf bound_ctrl:1
	s_nop 1
	v_or_b32_dpp v3, v3, v3 row_ror:1 row_mask:0xf bank_mask:0xf bound_ctrl:1
	s_nop 1
	v_readlane_b32 s4, v3, 0
	v_readlane_b32 s16, v3, 16
	s_or_b32 s4, s4, s16
	v_mbcnt_lo_u32_b32 v3, exec_lo, 0
	v_mbcnt_hi_u32_b32 v3, exec_hi, v3
	v_cmp_eq_u32_e32 vcc, 0, v3
	s_and_saveexec_b64 s[12:13], vcc
	s_xor_b64 s[12:13], exec, s[12:13]
	v_mov_b32_e32 v3, s4
	v_mov_b32_e32 v4, 0x24204
	ds_or_b32 v4, v3
	s_or_b64 exec, exec, s[12:13]
	v_add_u32_e32 v3, 0x24008, v2
	ds_read_b32 v3, v3
	s_mov_b64 s[12:13], exec
	s_mov_b32 s4, 0
	s_waitcnt lgkmcnt(0)
	v_or_b32_dpp v3, v3, v3 row_ror:8 row_mask:0xf bank_mask:0xf bound_ctrl:1
	s_nop 1
	v_or_b32_dpp v3, v3, v3 row_ror:4 row_mask:0xf bank_mask:0xf bound_ctrl:1
	s_nop 1
	v_or_b32_dpp v3, v3, v3 row_ror:2 row_mask:0xf bank_mask:0xf bound_ctrl:1
	s_nop 1
	v_or_b32_dpp v3, v3, v3 row_ror:1 row_mask:0xf bank_mask:0xf bound_ctrl:1
	s_nop 1
	v_readlane_b32 s4, v3, 0
	v_readlane_b32 s16, v3, 16
	s_or_b32 s4, s4, s16
	v_mbcnt_lo_u32_b32 v3, exec_lo, 0
	v_mbcnt_hi_u32_b32 v3, exec_hi, v3
	v_cmp_eq_u32_e32 vcc, 0, v3
	s_and_saveexec_b64 s[12:13], vcc
	s_xor_b64 s[12:13], exec, s[12:13]
	v_mov_b32_e32 v3, s4
	ds_or_b32 v230, v3
	s_or_b64 exec, exec, s[12:13]
	v_add_u32_e32 v2, 0x2400c, v2
	ds_read_b32 v2, v2
	s_mov_b64 s[12:13], exec
	s_mov_b32 s4, 0
	s_waitcnt lgkmcnt(0)
	v_or_b32_dpp v2, v2, v2 row_ror:8 row_mask:0xf bank_mask:0xf bound_ctrl:1
	s_nop 1
	v_or_b32_dpp v2, v2, v2 row_ror:4 row_mask:0xf bank_mask:0xf bound_ctrl:1
	s_nop 1
	v_or_b32_dpp v2, v2, v2 row_ror:2 row_mask:0xf bank_mask:0xf bound_ctrl:1
	s_nop 1
	v_or_b32_dpp v2, v2, v2 row_ror:1 row_mask:0xf bank_mask:0xf bound_ctrl:1
	s_nop 1
	v_readlane_b32 s4, v2, 0
	v_readlane_b32 s16, v2, 16
	s_or_b32 s4, s4, s16
	v_mbcnt_lo_u32_b32 v2, exec_lo, 0
	v_mbcnt_hi_u32_b32 v2, exec_hi, v2
	v_cmp_eq_u32_e32 vcc, 0, v2
	s_and_saveexec_b64 s[12:13], vcc
	s_xor_b64 s[12:13], exec, s[12:13]
	v_mov_b32_e32 v2, s4
	ds_or_b32 v231, v2
